# all sample skinny tiles (P1 in_proj, P4 GLU, P5 out_proj): fragments staged through LDS with coalesced LDS-DMA + ds_read_b128 instead of row-per-lane global loads
# speedup vs baseline: 1.0094x; 1.0002x over previous
.LBB0_1165:
	s_and_b32 s30, s25, 7
	s_lshl_b32 s18, s30, 16
	s_add_u32 s26, s44, s18
	v_mov_b32_e32 v1, v228
	s_addc_u32 s27, s45, 0
	s_and_b32 s18, s21, 0xffffffe0
	s_ashr_i32 s19, s18, 31
	v_and_b32_e32 v72, 31, v1
	v_ashrrev_i32_e32 v73, 5, v1
	s_lshl_b64 s[28:29], s[18:19], 10
	s_add_u32 s28, s8, s28
	s_addc_u32 s29, s9, s29
	s_mov_b32 s101, m0
	s_mul_i32 s100, s20, 0x180
	v_lshrrev_b32_e32 v24, 2, v1
	v_bfe_u32 v25, v1, 4, 2
	v_lshlrev_b32_e32 v24, 10, v24
	v_xor_b32_e32 v25, v25, v1
	v_bfe_u32 v26, v72, 2, 2
	v_and_b32_e32 v25, 3, v25
	v_xor_b32_e32 v26, v26, v73
	v_lshl_or_b32 v24, v25, 4, v24
	v_lshlrev_b32_e32 v26, 4, v26
	v_lshl_or_b32 v25, v72, 6, v26
	v_add_u32_e32 v25, s100, v25
	v_xor_b32_e32 v26, 32, v25
	s_add_u32 s98, s26, s4
	s_addc_u32 s99, s27, 0
	s_add_i32 m0, s100, 0x0
	s_nop 0
	global_load_lds_dwordx4 v24, s[98:99]
	s_add_u32 s98, s26, s4
	s_addc_u32 s99, s27, 0
	s_add_u32 s98, s98, 0x4000
	s_addc_u32 s99, s99, 0
	s_add_i32 m0, s100, 0x400
	s_nop 0
	global_load_lds_dwordx4 v24, s[98:99]
	s_add_u32 s98, s26, s4
	s_addc_u32 s99, s27, 0
	s_add_u32 s98, s98, 0x8000
	s_addc_u32 s99, s99, 0
	s_add_i32 m0, s100, 0x800
	s_nop 0
	global_load_lds_dwordx4 v24, s[98:99]
	s_add_u32 s98, s26, s4
	s_addc_u32 s99, s27, 0
	s_add_u32 s98, s98, 0xc000
	s_addc_u32 s99, s99, 0
	s_add_i32 m0, s100, 0xc00
	s_nop 0
	global_load_lds_dwordx4 v24, s[98:99]
	s_add_u32 s98, s28, s4
	s_addc_u32 s99, s29, 0
	s_add_u32 s98, s98, 0x1000000
	s_addc_u32 s99, s99, 0
	s_add_i32 m0, s100, 0x1000
	s_nop 0
	global_load_lds_dwordx4 v24, s[98:99]
	s_add_u32 s98, s28, s4
	s_addc_u32 s99, s29, 0
	s_add_u32 s98, s98, 0x1004000
	s_addc_u32 s99, s99, 0
	s_add_i32 m0, s100, 0x1400
	s_nop 0
	global_load_lds_dwordx4 v24, s[98:99]
	s_add_u32 s98, s26, s4
	s_addc_u32 s99, s27, 0
	s_add_u32 s98, s98, 0x40
	s_addc_u32 s99, s99, 0
	s_add_i32 m0, s100, 0x1800
	s_nop 0
	global_load_lds_dwordx4 v24, s[98:99]
	s_add_u32 s98, s26, s4
	s_addc_u32 s99, s27, 0
	s_add_u32 s98, s98, 0x4040
	s_addc_u32 s99, s99, 0
	s_add_i32 m0, s100, 0x1c00
	s_nop 0
	global_load_lds_dwordx4 v24, s[98:99]
	s_add_u32 s98, s26, s4
	s_addc_u32 s99, s27, 0
	s_add_u32 s98, s98, 0x8040
	s_addc_u32 s99, s99, 0
	s_add_i32 m0, s100, 0x2000
	s_nop 0
	global_load_lds_dwordx4 v24, s[98:99]
	s_add_u32 s98, s26, s4
	s_addc_u32 s99, s27, 0
	s_add_u32 s98, s98, 0xc040
	s_addc_u32 s99, s99, 0
	s_add_i32 m0, s100, 0x2400
	s_nop 0
	global_load_lds_dwordx4 v24, s[98:99]
	s_add_u32 s98, s28, s4
	s_addc_u32 s99, s29, 0
	s_add_u32 s98, s98, 0x1000040
	s_addc_u32 s99, s99, 0
	s_add_i32 m0, s100, 0x2800
	s_nop 0
	global_load_lds_dwordx4 v24, s[98:99]
	s_add_u32 s98, s28, s4
	s_addc_u32 s99, s29, 0
	s_add_u32 s98, s98, 0x1004040
	s_addc_u32 s99, s99, 0
	s_add_i32 m0, s100, 0x2c00
	s_nop 0
	global_load_lds_dwordx4 v24, s[98:99]
	s_waitcnt vmcnt(6)
	ds_read_b128 v[10:13], v25
	ds_read_b128 v[2:5], v25 offset:2048
	ds_read_b128 v[6:9], v25 offset:4096
	ds_read_b128 v[36:39], v26
	ds_read_b128 v[40:43], v26 offset:2048
	ds_read_b128 v[56:59], v26 offset:4096
	s_waitcnt vmcnt(0)
	ds_read_b128 v[48:51], v25 offset:6144
	ds_read_b128 v[44:47], v25 offset:8192
	ds_read_b128 v[64:67], v25 offset:10240
	ds_read_b128 v[52:55], v26 offset:6144
	ds_read_b128 v[60:63], v26 offset:8192
	ds_read_b128 v[68:71], v26 offset:10240
	s_mov_b32 m0, s101
	s_waitcnt lgkmcnt(0)
	v_mfma_f32_32x32x16_bf16 v[18:33], v[10:13], v[6:9], 0
	v_or_b32_e32 v34, s20, v72
	v_mul_lo_u32 v34, v34, s24
	s_add_u32 s18, s18, 0x4000
	s_addc_u32 s19, s19, 0
	s_add_i32 s25, s25, s46
	s_add_i32 s21, s21, s22
	s_cmpk_lt_i32 s25, 0x80
	v_mfma_f32_32x32x16_bf16 v[2:17], v[2:5], v[6:9], 0
	v_mfma_f32_32x32x16_bf16 v[18:33], v[36:39], v[56:59], v[18:33]
	v_lshlrev_b32_e32 v36, 4, v73
	v_add3_u32 v34, 0, v34, v36
	v_mfma_f32_32x32x16_bf16 v[2:17], v[40:43], v[56:59], v[2:17]
	v_mfma_f32_32x32x16_bf16 v[18:33], v[48:51], v[64:67], v[18:33]
	v_mfma_f32_32x32x16_bf16 v[2:17], v[44:47], v[64:67], v[2:17]
	v_mfma_f32_32x32x16_bf16 v[18:33], v[52:55], v[68:71], v[18:33]
	v_mfma_f32_32x32x16_bf16 v[2:17], v[60:63], v[68:71], v[2:17]
	s_nop 10
	s_barrier
	ds_write_b128 v34, v[18:21]
	ds_write_b128 v34, v[2:5] offset:128
	ds_write_b128 v34, v[22:25] offset:32
	ds_write_b128 v34, v[6:9] offset:160
	ds_write_b128 v34, v[26:29] offset:64
	ds_write_b128 v34, v[10:13] offset:192
	ds_write_b128 v34, v[30:33] offset:96
	ds_write_b128 v34, v[14:17] offset:224
	v_add_u32_e32 v2, s0, v1
	v_lshlrev_b32_e32 v1, 2, v1
	v_ashrrev_i32_e32 v36, 4, v2
	v_and_b32_e32 v1, 60, v1
	v_lshlrev_b32_e32 v2, 2, v1
	v_mul_lo_u32 v3, v36, s24
	v_lshl_or_b32 v1, s30, 6, v1
	v_add3_u32 v30, 0, v2, v3
	v_ashrrev_i32_e32 v37, 31, v36
	v_lshlrev_b32_e32 v34, 2, v1
	s_waitcnt lgkmcnt(0)
	s_barrier
	ds_read_b128 v[2:5], v30
	ds_read_b128 v[6:9], v30 offset:8704
	ds_read_b128 v[10:13], v30 offset:17408
	ds_read_b128 v[14:17], v30 offset:26112
	ds_read_b128 v[18:21], v30 offset:34816
	ds_read_b128 v[22:25], v30 offset:43520
	ds_read_b128 v[26:29], v30 offset:52224
	ds_read_b128 v[30:33], v30 offset:60928
	s_waitcnt lgkmcnt(0)
	s_barrier
	v_lshl_add_u64 v[40:41], s[18:19], 0, v[36:37]
	global_load_dwordx4 v[36:39], v34, s[56:57]
	v_lshlrev_b64 v[42:43], 10, v[40:41]
	v_lshl_add_u64 v[44:45], s[8:9], 0, v[42:43]
	v_lshlrev_b32_e32 v34, 1, v1
	v_lshl_add_u64 v[44:45], v[44:45], 0, v[34:35]
	v_lshl_add_u64 v[42:43], s[6:7], 0, v[42:43]
	global_load_dwordx2 v[44:45], v[44:45], off
	v_lshl_add_u64 v[42:43], v[42:43], 0, v[34:35]
	global_load_dwordx2 v[42:43], v[42:43], off
	v_pk_add_f32 v[4:5], v[4:5], 0 op_sel_hi:[1,0]
	v_pk_add_f32 v[2:3], v[2:3], 0 op_sel_hi:[1,0]
	v_pk_add_f32 v[4:5], v[4:5], v[8:9]
	v_pk_add_f32 v[2:3], v[2:3], v[6:7]
	v_pk_add_f32 v[4:5], v[4:5], v[12:13]
	v_pk_add_f32 v[2:3], v[2:3], v[10:11]
	v_pk_add_f32 v[4:5], v[4:5], v[16:17]
	v_pk_add_f32 v[2:3], v[2:3], v[14:15]
	v_pk_add_f32 v[4:5], v[4:5], v[20:21]
	v_pk_add_f32 v[2:3], v[2:3], v[18:19]
	v_pk_add_f32 v[4:5], v[4:5], v[24:25]
	v_pk_add_f32 v[2:3], v[2:3], v[22:23]
	v_pk_add_f32 v[4:5], v[4:5], v[28:29]
	v_pk_add_f32 v[2:3], v[2:3], v[26:27]
	v_pk_add_f32 v[4:5], v[4:5], v[32:33]
	v_pk_add_f32 v[2:3], v[2:3], v[30:31]
	v_lshlrev_b64 v[40:41], 11, v[40:41]
	v_lshl_add_u64 v[40:41], s[10:11], 0, v[40:41]
	v_lshl_add_u64 v[40:41], v[40:41], 0, v[34:35]
	s_waitcnt vmcnt(2)
	v_add_f32_e32 v2, v2, v36
	v_add_f32_e32 v3, v3, v37
	v_add_f32_e32 v4, v4, v38
	v_add_f32_e32 v5, v5, v39
	v_mul_f32_e32 v2, 0xbfb8aa3b, v2
	v_mul_f32_e32 v3, 0xbfb8aa3b, v3
	v_mul_f32_e32 v4, 0xbfb8aa3b, v4
	v_mul_f32_e32 v5, 0xbfb8aa3b, v5
	v_exp_f32_e32 v2, v2
	v_exp_f32_e32 v3, v3
	v_exp_f32_e32 v4, v4
	v_exp_f32_e32 v5, v5
	v_add_f32_e32 v2, 1.0, v2
	v_add_f32_e32 v3, 1.0, v3
	v_add_f32_e32 v4, 1.0, v4
	v_add_f32_e32 v5, 1.0, v5
	v_rcp_f32_e32 v2, v2
	v_rcp_f32_e32 v3, v3
	v_rcp_f32_e32 v4, v4
	v_rcp_f32_e32 v5, v5
	s_waitcnt vmcnt(1)
	v_lshlrev_b32_e32 v1, 16, v44
	v_and_b32_e32 v7, 0xffff0000, v44
	v_lshlrev_b32_e32 v9, 16, v45
	s_waitcnt vmcnt(0)
	v_and_b32_e32 v8, 0xffff0000, v42
	v_lshlrev_b32_e32 v10, 16, v43
	v_and_b32_e32 v11, 0xffff0000, v45
	v_mul_f32_e32 v1, v2, v1
	v_mul_f32_e32 v2, v3, v7
	v_mul_f32_e32 v3, v4, v9
	v_lshlrev_b32_e32 v6, 16, v42
	v_and_b32_e32 v12, 0xffff0000, v43
	v_mul_f32_e32 v4, v5, v11
	v_mul_f32_e32 v2, v2, v8
	v_mul_f32_e32 v3, v3, v10
	v_mul_f32_e32 v1, v1, v6
	v_mul_f32_e32 v4, v4, v12
	v_cvt_pk_bf16_f32 v2, v1, v2
	v_cvt_pk_bf16_f32 v3, v3, v4
	global_store_dwordx2 v[40:41], v[2:3], off offset:1024
	s_cbranch_scc1 .LBB0_1165

.LBB0_1187:
	s_and_b32 s23, s2, 7
	s_lshl_b32 s16, s23, 16
	s_add_u32 s24, s44, s16
	v_mov_b32_e32 v1, v228
	s_addc_u32 s25, s45, 0
	s_and_b32 s16, s19, 0xffffffe0
	s_ashr_i32 s17, s16, 31
	v_and_b32_e32 v72, 31, v1
	v_ashrrev_i32_e32 v73, 5, v1
	s_lshl_b64 s[26:27], s[16:17], 10
	s_add_u32 s26, s8, s26
	s_addc_u32 s27, s9, s27
	s_mov_b32 s101, m0
	s_mul_i32 s100, s18, 0x180
	v_lshrrev_b32_e32 v24, 2, v1
	v_bfe_u32 v25, v1, 4, 2
	v_lshlrev_b32_e32 v24, 10, v24
	v_xor_b32_e32 v25, v25, v1
	v_bfe_u32 v26, v72, 2, 2
	v_and_b32_e32 v25, 3, v25
	v_xor_b32_e32 v26, v26, v73
	v_lshl_or_b32 v24, v25, 4, v24
	v_lshlrev_b32_e32 v26, 4, v26
	v_lshl_or_b32 v25, v72, 6, v26
	v_add_u32_e32 v25, s100, v25
	v_xor_b32_e32 v26, 32, v25
	s_add_u32 s98, s24, s4
	s_addc_u32 s99, s25, 0
	s_add_i32 m0, s100, 0x0
	s_nop 0
	global_load_lds_dwordx4 v24, s[98:99]
	s_add_u32 s98, s24, s4
	s_addc_u32 s99, s25, 0
	s_add_u32 s98, s98, 0x4000
	s_addc_u32 s99, s99, 0
	s_add_i32 m0, s100, 0x400
	s_nop 0
	global_load_lds_dwordx4 v24, s[98:99]
	s_add_u32 s98, s24, s4
	s_addc_u32 s99, s25, 0
	s_add_u32 s98, s98, 0x8000
	s_addc_u32 s99, s99, 0
	s_add_i32 m0, s100, 0x800
	s_nop 0
	global_load_lds_dwordx4 v24, s[98:99]
	s_add_u32 s98, s24, s4
	s_addc_u32 s99, s25, 0
	s_add_u32 s98, s98, 0xc000
	s_addc_u32 s99, s99, 0
	s_add_i32 m0, s100, 0xc00
	s_nop 0
	global_load_lds_dwordx4 v24, s[98:99]
	s_add_u32 s98, s26, s4
	s_addc_u32 s99, s27, 0
	s_add_u32 s98, s98, 0x1000000
	s_addc_u32 s99, s99, 0
	s_add_i32 m0, s100, 0x1000
	s_nop 0
	global_load_lds_dwordx4 v24, s[98:99]
	s_add_u32 s98, s26, s4
	s_addc_u32 s99, s27, 0
	s_add_u32 s98, s98, 0x1004000
	s_addc_u32 s99, s99, 0
	s_add_i32 m0, s100, 0x1400
	s_nop 0
	global_load_lds_dwordx4 v24, s[98:99]
	s_add_u32 s98, s24, s4
	s_addc_u32 s99, s25, 0
	s_add_u32 s98, s98, 0x40
	s_addc_u32 s99, s99, 0
	s_add_i32 m0, s100, 0x1800
	s_nop 0
	global_load_lds_dwordx4 v24, s[98:99]
	s_add_u32 s98, s24, s4
	s_addc_u32 s99, s25, 0
	s_add_u32 s98, s98, 0x4040
	s_addc_u32 s99, s99, 0
	s_add_i32 m0, s100, 0x1c00
	s_nop 0
	global_load_lds_dwordx4 v24, s[98:99]
	s_add_u32 s98, s24, s4
	s_addc_u32 s99, s25, 0
	s_add_u32 s98, s98, 0x8040
	s_addc_u32 s99, s99, 0
	s_add_i32 m0, s100, 0x2000
	s_nop 0
	global_load_lds_dwordx4 v24, s[98:99]
	s_add_u32 s98, s24, s4
	s_addc_u32 s99, s25, 0
	s_add_u32 s98, s98, 0xc040
	s_addc_u32 s99, s99, 0
	s_add_i32 m0, s100, 0x2400
	s_nop 0
	global_load_lds_dwordx4 v24, s[98:99]
	s_add_u32 s98, s26, s4
	s_addc_u32 s99, s27, 0
	s_add_u32 s98, s98, 0x1000040
	s_addc_u32 s99, s99, 0
	s_add_i32 m0, s100, 0x2800
	s_nop 0
	global_load_lds_dwordx4 v24, s[98:99]
	s_add_u32 s98, s26, s4
	s_addc_u32 s99, s27, 0
	s_add_u32 s98, s98, 0x1004040
	s_addc_u32 s99, s99, 0
	s_add_i32 m0, s100, 0x2c00
	s_nop 0
	global_load_lds_dwordx4 v24, s[98:99]
	s_waitcnt vmcnt(6)
	ds_read_b128 v[10:13], v25
	ds_read_b128 v[2:5], v25 offset:2048
	ds_read_b128 v[6:9], v25 offset:4096
	ds_read_b128 v[36:39], v26
	ds_read_b128 v[40:43], v26 offset:2048
	ds_read_b128 v[56:59], v26 offset:4096
	s_waitcnt vmcnt(0)
	ds_read_b128 v[48:51], v25 offset:6144
	ds_read_b128 v[44:47], v25 offset:8192
	ds_read_b128 v[64:67], v25 offset:10240
	ds_read_b128 v[52:55], v26 offset:6144
	ds_read_b128 v[60:63], v26 offset:8192
	ds_read_b128 v[68:71], v26 offset:10240
	s_mov_b32 m0, s101
	s_waitcnt lgkmcnt(0)
	v_mfma_f32_32x32x16_bf16 v[18:33], v[10:13], v[6:9], 0
	v_or_b32_e32 v34, s18, v72
	v_mul_lo_u32 v34, v34, s22
	s_add_u32 s16, s16, 0x4000
	s_addc_u32 s17, s17, 0
	s_add_i32 s2, s2, s46
	s_add_i32 s19, s19, s20
	s_cmpk_lt_i32 s2, 0x80
	v_mfma_f32_32x32x16_bf16 v[2:17], v[2:5], v[6:9], 0
	v_mfma_f32_32x32x16_bf16 v[18:33], v[36:39], v[56:59], v[18:33]
	v_lshlrev_b32_e32 v36, 4, v73
	v_add3_u32 v34, 0, v34, v36
	v_mfma_f32_32x32x16_bf16 v[2:17], v[40:43], v[56:59], v[2:17]
	v_mfma_f32_32x32x16_bf16 v[18:33], v[48:51], v[64:67], v[18:33]
	v_mfma_f32_32x32x16_bf16 v[2:17], v[44:47], v[64:67], v[2:17]
	v_mfma_f32_32x32x16_bf16 v[18:33], v[52:55], v[68:71], v[18:33]
	v_mfma_f32_32x32x16_bf16 v[2:17], v[60:63], v[68:71], v[2:17]
	s_nop 10
	s_barrier
	ds_write_b128 v34, v[18:21]
	ds_write_b128 v34, v[2:5] offset:128
	ds_write_b128 v34, v[22:25] offset:32
	ds_write_b128 v34, v[6:9] offset:160
	ds_write_b128 v34, v[26:29] offset:64
	ds_write_b128 v34, v[10:13] offset:192
	ds_write_b128 v34, v[30:33] offset:96
	ds_write_b128 v34, v[14:17] offset:224
	v_add_u32_e32 v2, s0, v1
	v_lshlrev_b32_e32 v1, 2, v1
	v_ashrrev_i32_e32 v36, 4, v2
	v_and_b32_e32 v1, 60, v1
	v_lshlrev_b32_e32 v2, 2, v1
	v_mul_lo_u32 v3, v36, s22
	v_lshl_or_b32 v1, s23, 6, v1
	v_add3_u32 v30, 0, v2, v3
	v_ashrrev_i32_e32 v37, 31, v36
	v_lshlrev_b32_e32 v34, 2, v1
	s_waitcnt lgkmcnt(0)
	s_barrier
	ds_read_b128 v[2:5], v30
	ds_read_b128 v[6:9], v30 offset:8704
	ds_read_b128 v[10:13], v30 offset:17408
	ds_read_b128 v[14:17], v30 offset:26112
	ds_read_b128 v[18:21], v30 offset:34816
	ds_read_b128 v[22:25], v30 offset:43520
	ds_read_b128 v[26:29], v30 offset:52224
	ds_read_b128 v[30:33], v30 offset:60928
	s_waitcnt lgkmcnt(0)
	s_barrier
	v_lshl_add_u64 v[40:41], s[16:17], 0, v[36:37]
	global_load_dwordx4 v[36:39], v34, s[56:57]
	v_lshlrev_b64 v[42:43], 10, v[40:41]
	v_lshl_add_u64 v[44:45], s[8:9], 0, v[42:43]
	v_lshlrev_b32_e32 v34, 1, v1
	v_lshl_add_u64 v[44:45], v[44:45], 0, v[34:35]
	v_lshl_add_u64 v[42:43], s[6:7], 0, v[42:43]
	global_load_dwordx2 v[44:45], v[44:45], off
	v_lshl_add_u64 v[42:43], v[42:43], 0, v[34:35]
	global_load_dwordx2 v[42:43], v[42:43], off
	v_pk_add_f32 v[4:5], v[4:5], 0 op_sel_hi:[1,0]
	v_pk_add_f32 v[2:3], v[2:3], 0 op_sel_hi:[1,0]
	v_pk_add_f32 v[4:5], v[4:5], v[8:9]
	v_pk_add_f32 v[2:3], v[2:3], v[6:7]
	v_pk_add_f32 v[4:5], v[4:5], v[12:13]
	v_pk_add_f32 v[2:3], v[2:3], v[10:11]
	v_pk_add_f32 v[4:5], v[4:5], v[16:17]
	v_pk_add_f32 v[2:3], v[2:3], v[14:15]
	v_pk_add_f32 v[4:5], v[4:5], v[20:21]
	v_pk_add_f32 v[2:3], v[2:3], v[18:19]
	v_pk_add_f32 v[4:5], v[4:5], v[24:25]
	v_pk_add_f32 v[2:3], v[2:3], v[22:23]
	v_pk_add_f32 v[4:5], v[4:5], v[28:29]
	v_pk_add_f32 v[2:3], v[2:3], v[26:27]
	v_pk_add_f32 v[4:5], v[4:5], v[32:33]
	v_pk_add_f32 v[2:3], v[2:3], v[30:31]
	v_lshlrev_b64 v[40:41], 11, v[40:41]
	v_lshl_add_u64 v[40:41], s[10:11], 0, v[40:41]
	v_lshl_add_u64 v[40:41], v[40:41], 0, v[34:35]
	s_waitcnt vmcnt(2)
	v_add_f32_e32 v2, v2, v36
	v_add_f32_e32 v3, v3, v37
	v_add_f32_e32 v4, v4, v38
	v_add_f32_e32 v5, v5, v39
	v_mul_f32_e32 v2, 0xbfb8aa3b, v2
	v_mul_f32_e32 v3, 0xbfb8aa3b, v3
	v_mul_f32_e32 v4, 0xbfb8aa3b, v4
	v_mul_f32_e32 v5, 0xbfb8aa3b, v5
	v_exp_f32_e32 v2, v2
	v_exp_f32_e32 v3, v3
	v_exp_f32_e32 v4, v4
	v_exp_f32_e32 v5, v5
	v_add_f32_e32 v2, 1.0, v2
	v_add_f32_e32 v3, 1.0, v3
	v_add_f32_e32 v4, 1.0, v4
	v_add_f32_e32 v5, 1.0, v5
	v_rcp_f32_e32 v2, v2
	v_rcp_f32_e32 v3, v3
	v_rcp_f32_e32 v4, v4
	v_rcp_f32_e32 v5, v5
	s_waitcnt vmcnt(1)
	v_lshlrev_b32_e32 v1, 16, v44
	v_and_b32_e32 v7, 0xffff0000, v44
	v_lshlrev_b32_e32 v9, 16, v45
	s_waitcnt vmcnt(0)
	v_and_b32_e32 v8, 0xffff0000, v42
	v_lshlrev_b32_e32 v10, 16, v43
	v_and_b32_e32 v11, 0xffff0000, v45
	v_mul_f32_e32 v1, v2, v1
	v_mul_f32_e32 v2, v3, v7
	v_mul_f32_e32 v3, v4, v9
	v_lshlrev_b32_e32 v6, 16, v42
	v_and_b32_e32 v12, 0xffff0000, v43
	v_mul_f32_e32 v4, v5, v11
	v_mul_f32_e32 v2, v2, v8
	v_mul_f32_e32 v3, v3, v10
	v_mul_f32_e32 v1, v1, v6
	v_mul_f32_e32 v4, v4, v12
	v_cvt_pk_bf16_f32 v2, v1, v2
	v_cvt_pk_bf16_f32 v3, v3, v4
	global_store_dwordx2 v[40:41], v[2:3], off offset:1024
	s_cbranch_scc1 .LBB0_1187

.LBB0_1244:
	s_and_b32 s19, s18, 15
	s_ashr_i32 s12, s18, 4
	s_lshl_b32 s13, s19, 17
	s_add_u32 s20, s44, s13
	v_mov_b32_e32 v1, v228
	s_addc_u32 s21, s45, 0
	s_lshl_b32 s22, s12, 5
	s_ashr_i32 s23, s22, 31
	v_and_b32_e32 v120, 31, v1
	v_ashrrev_i32_e32 v121, 5, v1
	s_lshl_b64 s[22:23], s[22:23], 11
	s_add_u32 s22, s46, s22
	s_addc_u32 s23, s47, s23
	s_mov_b32 s101, m0
	s_mul_i32 s100, s2, 0x180
	v_lshrrev_b32_e32 v24, 2, v1
	v_bfe_u32 v25, v1, 4, 2
	v_lshlrev_b32_e32 v24, 11, v24
	v_xor_b32_e32 v25, v25, v1
	v_bfe_u32 v26, v120, 2, 2
	v_and_b32_e32 v25, 3, v25
	v_xor_b32_e32 v26, v26, v121
	v_lshl_or_b32 v24, v25, 4, v24
	v_lshlrev_b32_e32 v26, 4, v26
	v_lshl_or_b32 v25, v120, 6, v26
	v_add_u32_e32 v25, s100, v25
	v_xor_b32_e32 v26, 32, v25
	s_add_u32 s98, s20, s4
	s_addc_u32 s99, s21, 0
	s_add_i32 m0, s100, 0x0
	s_nop 0
	global_load_lds_dwordx4 v24, s[98:99]
	s_add_u32 s98, s20, s4
	s_addc_u32 s99, s21, 0
	s_add_u32 s98, s98, 0x8000
	s_addc_u32 s99, s99, 0
	s_add_i32 m0, s100, 0x400
	s_nop 0
	global_load_lds_dwordx4 v24, s[98:99]
	s_add_u32 s98, s20, s4
	s_addc_u32 s99, s21, 0
	s_add_u32 s98, s98, 0x10000
	s_addc_u32 s99, s99, 0
	s_add_i32 m0, s100, 0x800
	s_nop 0
	global_load_lds_dwordx4 v24, s[98:99]
	s_add_u32 s98, s20, s4
	s_addc_u32 s99, s21, 0
	s_add_u32 s98, s98, 0x18000
	s_addc_u32 s99, s99, 0
	s_add_i32 m0, s100, 0xc00
	s_nop 0
	global_load_lds_dwordx4 v24, s[98:99]
	s_add_u32 s98, s22, s4
	s_addc_u32 s99, s23, 0
	s_add_u32 s98, s98, 0x2000000
	s_addc_u32 s99, s99, 0
	s_add_i32 m0, s100, 0x1000
	s_nop 0
	global_load_lds_dwordx4 v24, s[98:99]
	s_add_u32 s98, s22, s4
	s_addc_u32 s99, s23, 0
	s_add_u32 s98, s98, 0x2008000
	s_addc_u32 s99, s99, 0
	s_add_i32 m0, s100, 0x1400
	s_nop 0
	global_load_lds_dwordx4 v24, s[98:99]
	s_add_u32 s98, s20, s4
	s_addc_u32 s99, s21, 0
	s_add_u32 s98, s98, 0x40
	s_addc_u32 s99, s99, 0
	s_add_i32 m0, s100, 0x1800
	s_nop 0
	global_load_lds_dwordx4 v24, s[98:99]
	s_add_u32 s98, s20, s4
	s_addc_u32 s99, s21, 0
	s_add_u32 s98, s98, 0x8040
	s_addc_u32 s99, s99, 0
	s_add_i32 m0, s100, 0x1c00
	s_nop 0
	global_load_lds_dwordx4 v24, s[98:99]
	s_add_u32 s98, s20, s4
	s_addc_u32 s99, s21, 0
	s_add_u32 s98, s98, 0x10040
	s_addc_u32 s99, s99, 0
	s_add_i32 m0, s100, 0x2000
	s_nop 0
	global_load_lds_dwordx4 v24, s[98:99]
	s_add_u32 s98, s20, s4
	s_addc_u32 s99, s21, 0
	s_add_u32 s98, s98, 0x18040
	s_addc_u32 s99, s99, 0
	s_add_i32 m0, s100, 0x2400
	s_nop 0
	global_load_lds_dwordx4 v24, s[98:99]
	s_add_u32 s98, s22, s4
	s_addc_u32 s99, s23, 0
	s_add_u32 s98, s98, 0x2000040
	s_addc_u32 s99, s99, 0
	s_add_i32 m0, s100, 0x2800
	s_nop 0
	global_load_lds_dwordx4 v24, s[98:99]
	s_add_u32 s98, s22, s4
	s_addc_u32 s99, s23, 0
	s_add_u32 s98, s98, 0x2008040
	s_addc_u32 s99, s99, 0
	s_add_i32 m0, s100, 0x2c00
	s_nop 0
	global_load_lds_dwordx4 v24, s[98:99]
	s_waitcnt vmcnt(6)
	ds_read_b128 v[10:13], v25
	ds_read_b128 v[2:5], v25 offset:2048
	ds_read_b128 v[6:9], v25 offset:4096
	ds_read_b128 v[36:39], v26
	ds_read_b128 v[40:43], v26 offset:2048
	ds_read_b128 v[104:107], v26 offset:4096
	s_waitcnt lgkmcnt(0)
	s_add_u32 s98, s20, s4
	s_addc_u32 s99, s21, 0
	s_add_u32 s98, s98, 0x80
	s_addc_u32 s99, s99, 0
	s_add_i32 m0, s100, 0x0
	s_nop 0
	global_load_lds_dwordx4 v24, s[98:99]
	s_add_u32 s98, s20, s4
	s_addc_u32 s99, s21, 0
	s_add_u32 s98, s98, 0x8080
	s_addc_u32 s99, s99, 0
	s_add_i32 m0, s100, 0x400
	s_nop 0
	global_load_lds_dwordx4 v24, s[98:99]
	s_add_u32 s98, s20, s4
	s_addc_u32 s99, s21, 0
	s_add_u32 s98, s98, 0x10080
	s_addc_u32 s99, s99, 0
	s_add_i32 m0, s100, 0x800
	s_nop 0
	global_load_lds_dwordx4 v24, s[98:99]
	s_add_u32 s98, s20, s4
	s_addc_u32 s99, s21, 0
	s_add_u32 s98, s98, 0x18080
	s_addc_u32 s99, s99, 0
	s_add_i32 m0, s100, 0xc00
	s_nop 0
	global_load_lds_dwordx4 v24, s[98:99]
	s_add_u32 s98, s22, s4
	s_addc_u32 s99, s23, 0
	s_add_u32 s98, s98, 0x2000080
	s_addc_u32 s99, s99, 0
	s_add_i32 m0, s100, 0x1000
	s_nop 0
	global_load_lds_dwordx4 v24, s[98:99]
	s_add_u32 s98, s22, s4
	s_addc_u32 s99, s23, 0
	s_add_u32 s98, s98, 0x2008080
	s_addc_u32 s99, s99, 0
	s_add_i32 m0, s100, 0x1400
	s_nop 0
	global_load_lds_dwordx4 v24, s[98:99]
	s_waitcnt vmcnt(6)
	ds_read_b128 v[48:51], v25 offset:6144
	ds_read_b128 v[44:47], v25 offset:8192
	ds_read_b128 v[56:59], v25 offset:10240
	ds_read_b128 v[52:55], v26 offset:6144
	ds_read_b128 v[64:67], v26 offset:8192
	ds_read_b128 v[60:63], v26 offset:10240
	s_waitcnt lgkmcnt(0)
	s_add_u32 s98, s20, s4
	s_addc_u32 s99, s21, 0
	s_add_u32 s98, s98, 0xc0
	s_addc_u32 s99, s99, 0
	s_add_i32 m0, s100, 0x1800
	s_nop 0
	global_load_lds_dwordx4 v24, s[98:99]
	s_add_u32 s98, s20, s4
	s_addc_u32 s99, s21, 0
	s_add_u32 s98, s98, 0x80c0
	s_addc_u32 s99, s99, 0
	s_add_i32 m0, s100, 0x1c00
	s_nop 0
	global_load_lds_dwordx4 v24, s[98:99]
	s_add_u32 s98, s20, s4
	s_addc_u32 s99, s21, 0
	s_add_u32 s98, s98, 0x100c0
	s_addc_u32 s99, s99, 0
	s_add_i32 m0, s100, 0x2000
	s_nop 0
	global_load_lds_dwordx4 v24, s[98:99]
	s_add_u32 s98, s20, s4
	s_addc_u32 s99, s21, 0
	s_add_u32 s98, s98, 0x180c0
	s_addc_u32 s99, s99, 0
	s_add_i32 m0, s100, 0x2400
	s_nop 0
	global_load_lds_dwordx4 v24, s[98:99]
	s_add_u32 s98, s22, s4
	s_addc_u32 s99, s23, 0
	s_add_u32 s98, s98, 0x20000c0
	s_addc_u32 s99, s99, 0
	s_add_i32 m0, s100, 0x2800
	s_nop 0
	global_load_lds_dwordx4 v24, s[98:99]
	s_add_u32 s98, s22, s4
	s_addc_u32 s99, s23, 0
	s_add_u32 s98, s98, 0x20080c0
	s_addc_u32 s99, s99, 0
	s_add_i32 m0, s100, 0x2c00
	s_nop 0
	global_load_lds_dwordx4 v24, s[98:99]
	s_waitcnt vmcnt(6)
	ds_read_b128 v[72:75], v25
	ds_read_b128 v[68:71], v25 offset:2048
	ds_read_b128 v[80:83], v25 offset:4096
	ds_read_b128 v[76:79], v26
	ds_read_b128 v[88:91], v26 offset:2048
	ds_read_b128 v[84:87], v26 offset:4096
	s_waitcnt vmcnt(0)
	ds_read_b128 v[96:99], v25 offset:6144
	ds_read_b128 v[92:95], v25 offset:8192
	ds_read_b128 v[112:115], v25 offset:10240
	ds_read_b128 v[100:103], v26 offset:6144
	ds_read_b128 v[108:111], v26 offset:8192
	ds_read_b128 v[116:119], v26 offset:10240
	s_mov_b32 m0, s101
	s_waitcnt lgkmcnt(0)
	v_mfma_f32_32x32x16_bf16 v[18:33], v[10:13], v[6:9], 0
	v_or_b32_e32 v34, s2, v120
	v_mul_lo_u32 v34, v34, s17
	s_and_b64 vcc, exec, s[0:1]
	v_mfma_f32_32x32x16_bf16 v[2:17], v[2:5], v[6:9], 0
	v_mfma_f32_32x32x16_bf16 v[18:33], v[36:39], v[104:107], v[18:33]
	v_lshlrev_b32_e32 v36, 4, v121
	v_add3_u32 v34, 0, v34, v36
	v_mfma_f32_32x32x16_bf16 v[2:17], v[40:43], v[104:107], v[2:17]
	v_mfma_f32_32x32x16_bf16 v[18:33], v[48:51], v[56:59], v[18:33]
	v_mfma_f32_32x32x16_bf16 v[2:17], v[44:47], v[56:59], v[2:17]
	v_mfma_f32_32x32x16_bf16 v[18:33], v[52:55], v[60:63], v[18:33]
	v_mfma_f32_32x32x16_bf16 v[2:17], v[64:67], v[60:63], v[2:17]
	v_mfma_f32_32x32x16_bf16 v[18:33], v[72:75], v[80:83], v[18:33]
	v_mfma_f32_32x32x16_bf16 v[2:17], v[68:71], v[80:83], v[2:17]
	v_mfma_f32_32x32x16_bf16 v[18:33], v[76:79], v[84:87], v[18:33]
	v_mfma_f32_32x32x16_bf16 v[2:17], v[88:91], v[84:87], v[2:17]
	v_mfma_f32_32x32x16_bf16 v[18:33], v[96:99], v[112:115], v[18:33]
	v_mfma_f32_32x32x16_bf16 v[2:17], v[92:95], v[112:115], v[2:17]
	v_mfma_f32_32x32x16_bf16 v[18:33], v[100:103], v[116:119], v[18:33]
	v_mfma_f32_32x32x16_bf16 v[2:17], v[108:111], v[116:119], v[2:17]
	s_nop 10
	s_barrier
	ds_write_b128 v34, v[18:21]
	ds_write_b128 v34, v[2:5] offset:128
	ds_write_b128 v34, v[22:25] offset:32
	ds_write_b128 v34, v[6:9] offset:160
	ds_write_b128 v34, v[26:29] offset:64
	ds_write_b128 v34, v[10:13] offset:192
	ds_write_b128 v34, v[30:33] offset:96
	ds_write_b128 v34, v[14:17] offset:224
	v_add_u32_e32 v2, s14, v1
	v_lshlrev_b32_e32 v1, 2, v1
	v_ashrrev_i32_e32 v36, 4, v2
	v_and_b32_e32 v1, 60, v1
	v_lshlrev_b32_e32 v1, 2, v1
	v_mul_lo_u32 v2, v36, s17
	v_add3_u32 v2, 0, v1, v2
	s_waitcnt lgkmcnt(0)
	s_barrier
	ds_read_b128 v[30:33], v2
	ds_read_b128 v[26:29], v2 offset:8704
	ds_read_b128 v[22:25], v2 offset:17408
	ds_read_b128 v[18:21], v2 offset:26112
	ds_read_b128 v[14:17], v2 offset:34816
	ds_read_b128 v[10:13], v2 offset:43520
	ds_read_b128 v[6:9], v2 offset:52224
	ds_read_b128 v[2:5], v2 offset:60928
	s_waitcnt lgkmcnt(0)
	s_barrier
	s_cbranch_vccnz .LBB0_1243
	s_ashr_i32 s13, s12, 31
	v_ashrrev_i32_e32 v37, 31, v36
	s_lshl_b64 s[12:13], s[12:13], 15
	v_lshlrev_b64 v[36:37], 10, v[36:37]
	v_lshl_add_u64 v[36:37], v[36:37], 0, s[12:13]
	v_lshlrev_b64 v[40:41], 2, v[36:37]
	v_lshl_add_u64 v[36:37], s[42:43], 0, v[40:41]
	v_lshl_or_b32 v34, s19, 8, v1
	v_lshl_add_u64 v[36:37], v[36:37], 0, v[34:35]
	global_load_dwordx4 v[36:39], v[36:37], off
	v_pk_add_f32 v[32:33], v[32:33], 0 op_sel_hi:[1,0]
	v_pk_add_f32 v[30:31], v[30:31], 0 op_sel_hi:[1,0]
	v_pk_add_f32 v[28:29], v[32:33], v[28:29]
	v_pk_add_f32 v[26:27], v[30:31], v[26:27]
	v_pk_add_f32 v[24:25], v[28:29], v[24:25]
	v_pk_add_f32 v[22:23], v[26:27], v[22:23]
	v_pk_add_f32 v[20:21], v[24:25], v[20:21]
	v_pk_add_f32 v[18:19], v[22:23], v[18:19]
	v_pk_add_f32 v[16:17], v[20:21], v[16:17]
	v_pk_add_f32 v[14:15], v[18:19], v[14:15]
	v_pk_add_f32 v[12:13], v[16:17], v[12:13]
	v_pk_add_f32 v[10:11], v[14:15], v[10:11]
	v_pk_add_f32 v[8:9], v[12:13], v[8:9]
	v_pk_add_f32 v[6:7], v[10:11], v[6:7]
	v_lshl_add_u64 v[18:19], s[6:7], 0, v[40:41]
	v_pk_add_f32 v[4:5], v[8:9], v[4:5]
	v_pk_add_f32 v[2:3], v[6:7], v[2:3]
	v_lshl_add_u64 v[6:7], v[18:19], 0, v[34:35]
	s_waitcnt vmcnt(0)
	v_pk_add_f32 v[4:5], v[4:5], v[38:39]
	v_pk_add_f32 v[2:3], v[2:3], v[36:37]
	global_store_dwordx4 v[6:7], v[2:5], off
	s_branch .LBB0_1243

.LBB0_1276:
	s_and_b32 s17, s88, 15
	s_ashr_i32 s10, s88, 4
	s_lshl_b32 s11, s17, 17
	s_add_u32 s18, s44, s11
	v_mov_b32_e32 v118, v228
	s_addc_u32 s19, s45, 0
	s_lshl_b32 s20, s10, 5
	s_ashr_i32 s21, s20, 31
	v_and_b32_e32 v119, 31, v118
	v_ashrrev_i32_e32 v120, 5, v118
	s_lshl_b64 s[20:21], s[20:21], 11
	s_add_u32 s20, s46, s20
	s_addc_u32 s21, s47, s21
	s_mov_b32 s101, m0
	s_mul_i32 s100, s12, 0x180
	v_lshrrev_b32_e32 v22, 2, v118
	v_bfe_u32 v23, v118, 4, 2
	v_lshlrev_b32_e32 v22, 11, v22
	v_xor_b32_e32 v23, v23, v118
	v_bfe_u32 v24, v119, 2, 2
	v_and_b32_e32 v23, 3, v23
	v_xor_b32_e32 v24, v24, v120
	v_lshl_or_b32 v22, v23, 4, v22
	v_lshlrev_b32_e32 v24, 4, v24
	v_lshl_or_b32 v23, v119, 6, v24
	v_add_u32_e32 v23, s100, v23
	v_xor_b32_e32 v24, 32, v23
	s_add_u32 s98, s18, s2
	s_addc_u32 s99, s19, 0
	s_add_i32 m0, s100, 0x0
	s_nop 0
	global_load_lds_dwordx4 v22, s[98:99]
	s_add_u32 s98, s18, s2
	s_addc_u32 s99, s19, 0
	s_add_u32 s98, s98, 0x8000
	s_addc_u32 s99, s99, 0
	s_add_i32 m0, s100, 0x400
	s_nop 0
	global_load_lds_dwordx4 v22, s[98:99]
	s_add_u32 s98, s18, s2
	s_addc_u32 s99, s19, 0
	s_add_u32 s98, s98, 0x10000
	s_addc_u32 s99, s99, 0
	s_add_i32 m0, s100, 0x800
	s_nop 0
	global_load_lds_dwordx4 v22, s[98:99]
	s_add_u32 s98, s18, s2
	s_addc_u32 s99, s19, 0
	s_add_u32 s98, s98, 0x18000
	s_addc_u32 s99, s99, 0
	s_add_i32 m0, s100, 0xc00
	s_nop 0
	global_load_lds_dwordx4 v22, s[98:99]
	s_add_u32 s98, s20, s2
	s_addc_u32 s99, s21, 0
	s_add_u32 s98, s98, 0x2000000
	s_addc_u32 s99, s99, 0
	s_add_i32 m0, s100, 0x1000
	s_nop 0
	global_load_lds_dwordx4 v22, s[98:99]
	s_add_u32 s98, s20, s2
	s_addc_u32 s99, s21, 0
	s_add_u32 s98, s98, 0x2008000
	s_addc_u32 s99, s99, 0
	s_add_i32 m0, s100, 0x1400
	s_nop 0
	global_load_lds_dwordx4 v22, s[98:99]
	s_add_u32 s98, s18, s2
	s_addc_u32 s99, s19, 0
	s_add_u32 s98, s98, 0x40
	s_addc_u32 s99, s99, 0
	s_add_i32 m0, s100, 0x1800
	s_nop 0
	global_load_lds_dwordx4 v22, s[98:99]
	s_add_u32 s98, s18, s2
	s_addc_u32 s99, s19, 0
	s_add_u32 s98, s98, 0x8040
	s_addc_u32 s99, s99, 0
	s_add_i32 m0, s100, 0x1c00
	s_nop 0
	global_load_lds_dwordx4 v22, s[98:99]
	s_add_u32 s98, s18, s2
	s_addc_u32 s99, s19, 0
	s_add_u32 s98, s98, 0x10040
	s_addc_u32 s99, s99, 0
	s_add_i32 m0, s100, 0x2000
	s_nop 0
	global_load_lds_dwordx4 v22, s[98:99]
	s_add_u32 s98, s18, s2
	s_addc_u32 s99, s19, 0
	s_add_u32 s98, s98, 0x18040
	s_addc_u32 s99, s99, 0
	s_add_i32 m0, s100, 0x2400
	s_nop 0
	global_load_lds_dwordx4 v22, s[98:99]
	s_add_u32 s98, s20, s2
	s_addc_u32 s99, s21, 0
	s_add_u32 s98, s98, 0x2000040
	s_addc_u32 s99, s99, 0
	s_add_i32 m0, s100, 0x2800
	s_nop 0
	global_load_lds_dwordx4 v22, s[98:99]
	s_add_u32 s98, s20, s2
	s_addc_u32 s99, s21, 0
	s_add_u32 s98, s98, 0x2008040
	s_addc_u32 s99, s99, 0
	s_add_i32 m0, s100, 0x2c00
	s_nop 0
	global_load_lds_dwordx4 v22, s[98:99]
	s_waitcnt vmcnt(6)
	ds_read_b128 v[8:11], v23
	ds_read_b128 v[0:3], v23 offset:2048
	ds_read_b128 v[4:7], v23 offset:4096
	ds_read_b128 v[34:37], v24
	ds_read_b128 v[38:41], v24 offset:2048
	ds_read_b128 v[102:105], v24 offset:4096
	s_waitcnt lgkmcnt(0)
	s_add_u32 s98, s18, s2
	s_addc_u32 s99, s19, 0
	s_add_u32 s98, s98, 0x80
	s_addc_u32 s99, s99, 0
	s_add_i32 m0, s100, 0x0
	s_nop 0
	global_load_lds_dwordx4 v22, s[98:99]
	s_add_u32 s98, s18, s2
	s_addc_u32 s99, s19, 0
	s_add_u32 s98, s98, 0x8080
	s_addc_u32 s99, s99, 0
	s_add_i32 m0, s100, 0x400
	s_nop 0
	global_load_lds_dwordx4 v22, s[98:99]
	s_add_u32 s98, s18, s2
	s_addc_u32 s99, s19, 0
	s_add_u32 s98, s98, 0x10080
	s_addc_u32 s99, s99, 0
	s_add_i32 m0, s100, 0x800
	s_nop 0
	global_load_lds_dwordx4 v22, s[98:99]
	s_add_u32 s98, s18, s2
	s_addc_u32 s99, s19, 0
	s_add_u32 s98, s98, 0x18080
	s_addc_u32 s99, s99, 0
	s_add_i32 m0, s100, 0xc00
	s_nop 0
	global_load_lds_dwordx4 v22, s[98:99]
	s_add_u32 s98, s20, s2
	s_addc_u32 s99, s21, 0
	s_add_u32 s98, s98, 0x2000080
	s_addc_u32 s99, s99, 0
	s_add_i32 m0, s100, 0x1000
	s_nop 0
	global_load_lds_dwordx4 v22, s[98:99]
	s_add_u32 s98, s20, s2
	s_addc_u32 s99, s21, 0
	s_add_u32 s98, s98, 0x2008080
	s_addc_u32 s99, s99, 0
	s_add_i32 m0, s100, 0x1400
	s_nop 0
	global_load_lds_dwordx4 v22, s[98:99]
	s_waitcnt vmcnt(6)
	ds_read_b128 v[46:49], v23 offset:6144
	ds_read_b128 v[42:45], v23 offset:8192
	ds_read_b128 v[54:57], v23 offset:10240
	ds_read_b128 v[50:53], v24 offset:6144
	ds_read_b128 v[62:65], v24 offset:8192
	ds_read_b128 v[58:61], v24 offset:10240
	s_waitcnt lgkmcnt(0)
	s_add_u32 s98, s18, s2
	s_addc_u32 s99, s19, 0
	s_add_u32 s98, s98, 0xc0
	s_addc_u32 s99, s99, 0
	s_add_i32 m0, s100, 0x1800
	s_nop 0
	global_load_lds_dwordx4 v22, s[98:99]
	s_add_u32 s98, s18, s2
	s_addc_u32 s99, s19, 0
	s_add_u32 s98, s98, 0x80c0
	s_addc_u32 s99, s99, 0
	s_add_i32 m0, s100, 0x1c00
	s_nop 0
	global_load_lds_dwordx4 v22, s[98:99]
	s_add_u32 s98, s18, s2
	s_addc_u32 s99, s19, 0
	s_add_u32 s98, s98, 0x100c0
	s_addc_u32 s99, s99, 0
	s_add_i32 m0, s100, 0x2000
	s_nop 0
	global_load_lds_dwordx4 v22, s[98:99]
	s_add_u32 s98, s18, s2
	s_addc_u32 s99, s19, 0
	s_add_u32 s98, s98, 0x180c0
	s_addc_u32 s99, s99, 0
	s_add_i32 m0, s100, 0x2400
	s_nop 0
	global_load_lds_dwordx4 v22, s[98:99]
	s_add_u32 s98, s20, s2
	s_addc_u32 s99, s21, 0
	s_add_u32 s98, s98, 0x20000c0
	s_addc_u32 s99, s99, 0
	s_add_i32 m0, s100, 0x2800
	s_nop 0
	global_load_lds_dwordx4 v22, s[98:99]
	s_add_u32 s98, s20, s2
	s_addc_u32 s99, s21, 0
	s_add_u32 s98, s98, 0x20080c0
	s_addc_u32 s99, s99, 0
	s_add_i32 m0, s100, 0x2c00
	s_nop 0
	global_load_lds_dwordx4 v22, s[98:99]
	s_waitcnt vmcnt(6)
	ds_read_b128 v[70:73], v23
	ds_read_b128 v[66:69], v23 offset:2048
	ds_read_b128 v[78:81], v23 offset:4096
	ds_read_b128 v[74:77], v24
	ds_read_b128 v[86:89], v24 offset:2048
	ds_read_b128 v[82:85], v24 offset:4096
	s_waitcnt vmcnt(0)
	ds_read_b128 v[94:97], v23 offset:6144
	ds_read_b128 v[90:93], v23 offset:8192
	ds_read_b128 v[110:113], v23 offset:10240
	ds_read_b128 v[98:101], v24 offset:6144
	ds_read_b128 v[106:109], v24 offset:8192
	ds_read_b128 v[114:117], v24 offset:10240
	s_mov_b32 m0, s101
	s_waitcnt lgkmcnt(0)
	v_mfma_f32_32x32x16_bf16 v[16:31], v[8:11], v[4:7], 0
	v_or_b32_e32 v32, s12, v119
	v_mul_lo_u32 v32, v32, s16
	s_and_b64 vcc, exec, s[0:1]
	v_mfma_f32_32x32x16_bf16 v[0:15], v[0:3], v[4:7], 0
	v_mfma_f32_32x32x16_bf16 v[16:31], v[34:37], v[102:105], v[16:31]
	v_lshlrev_b32_e32 v34, 4, v120
	v_add3_u32 v32, 0, v32, v34
	v_mfma_f32_32x32x16_bf16 v[0:15], v[38:41], v[102:105], v[0:15]
	v_mfma_f32_32x32x16_bf16 v[16:31], v[46:49], v[54:57], v[16:31]
	v_mfma_f32_32x32x16_bf16 v[0:15], v[42:45], v[54:57], v[0:15]
	v_mfma_f32_32x32x16_bf16 v[16:31], v[50:53], v[58:61], v[16:31]
	v_mfma_f32_32x32x16_bf16 v[0:15], v[62:65], v[58:61], v[0:15]
	v_mfma_f32_32x32x16_bf16 v[16:31], v[70:73], v[78:81], v[16:31]
	v_mfma_f32_32x32x16_bf16 v[0:15], v[66:69], v[78:81], v[0:15]
	v_mfma_f32_32x32x16_bf16 v[16:31], v[74:77], v[82:85], v[16:31]
	v_mfma_f32_32x32x16_bf16 v[0:15], v[86:89], v[82:85], v[0:15]
	v_mfma_f32_32x32x16_bf16 v[16:31], v[94:97], v[110:113], v[16:31]
	v_mfma_f32_32x32x16_bf16 v[0:15], v[90:93], v[110:113], v[0:15]
	v_mfma_f32_32x32x16_bf16 v[16:31], v[98:101], v[114:117], v[16:31]
	v_mfma_f32_32x32x16_bf16 v[0:15], v[106:109], v[114:117], v[0:15]
	s_nop 10
	s_barrier
	ds_write_b128 v32, v[16:19]
	ds_write_b128 v32, v[0:3] offset:128
	ds_write_b128 v32, v[20:23] offset:32
	ds_write_b128 v32, v[4:7] offset:160
	ds_write_b128 v32, v[24:27] offset:64
	ds_write_b128 v32, v[8:11] offset:192
	ds_write_b128 v32, v[28:31] offset:96
	ds_write_b128 v32, v[12:15] offset:224
	v_add_u32_e32 v0, s13, v118
	v_ashrrev_i32_e32 v34, 4, v0
	v_lshlrev_b32_e32 v0, 2, v118
	v_and_b32_e32 v0, 60, v0
	v_lshlrev_b32_e32 v32, 2, v0
	v_mul_lo_u32 v0, v34, s16
	v_add3_u32 v0, 0, v32, v0
	s_waitcnt lgkmcnt(0)
	s_barrier
	ds_read_b128 v[28:31], v0
	ds_read_b128 v[24:27], v0 offset:8704
	ds_read_b128 v[20:23], v0 offset:17408
	ds_read_b128 v[16:19], v0 offset:26112
	ds_read_b128 v[12:15], v0 offset:34816
	ds_read_b128 v[8:11], v0 offset:43520
	ds_read_b128 v[4:7], v0 offset:52224
	ds_read_b128 v[0:3], v0 offset:60928
	s_waitcnt lgkmcnt(0)
	s_barrier
	s_cbranch_vccnz .LBB0_1275
	s_ashr_i32 s11, s10, 31
	v_ashrrev_i32_e32 v35, 31, v34
	s_lshl_b64 s[10:11], s[10:11], 15
	v_lshlrev_b64 v[34:35], 10, v[34:35]
	v_lshl_add_u64 v[34:35], v[34:35], 0, s[10:11]
	v_lshlrev_b64 v[38:39], 2, v[34:35]
	v_lshl_add_u64 v[34:35], s[42:43], 0, v[38:39]
	v_lshl_or_b32 v32, s17, 8, v32
	v_lshl_add_u64 v[34:35], v[34:35], 0, v[32:33]
	global_load_dwordx4 v[34:37], v[34:35], off
	v_pk_add_f32 v[30:31], v[30:31], 0 op_sel_hi:[1,0]
	v_pk_add_f32 v[28:29], v[28:29], 0 op_sel_hi:[1,0]
	v_pk_add_f32 v[26:27], v[30:31], v[26:27]
	v_pk_add_f32 v[24:25], v[28:29], v[24:25]
	v_pk_add_f32 v[22:23], v[26:27], v[22:23]
	v_pk_add_f32 v[20:21], v[24:25], v[20:21]
	v_pk_add_f32 v[18:19], v[22:23], v[18:19]
	v_pk_add_f32 v[16:17], v[20:21], v[16:17]
	v_pk_add_f32 v[14:15], v[18:19], v[14:15]
	v_pk_add_f32 v[12:13], v[16:17], v[12:13]
	v_pk_add_f32 v[10:11], v[14:15], v[10:11]
	v_pk_add_f32 v[8:9], v[12:13], v[8:9]
	v_pk_add_f32 v[6:7], v[10:11], v[6:7]
	v_pk_add_f32 v[4:5], v[8:9], v[4:5]
	v_lshl_add_u64 v[16:17], s[4:5], 0, v[38:39]
	v_pk_add_f32 v[2:3], v[6:7], v[2:3]
	v_pk_add_f32 v[0:1], v[4:5], v[0:1]
	v_lshl_add_u64 v[4:5], v[16:17], 0, v[32:33]
	s_waitcnt vmcnt(0)
	v_pk_add_f32 v[2:3], v[2:3], v[36:37]
	v_pk_add_f32 v[0:1], v[0:1], v[34:35]
	global_store_dwordx4 v[4:5], v[0:3], off
	s_branch .LBB0_1275
